# v18 + down-projection GEMMs (P9, P21) tile-group height WGM 2 -> 4
# baseline (speedup 1.0000x reference)
.LBB0_939:
	s_ashr_i32 s7, s2, 3
	s_add_u32 s21, s74, 0x23510000
	s_addc_u32 s30, s75, 0
	s_add_u32 s31, s74, 0x4a110000
	s_addc_u32 s33, s75, 0
	s_add_i32 s7, s9, s7
	v_lshlrev_b32_e32 v2, 4, v0
	v_and_b32_e32 v3, 32, v0
	s_ashr_i32 s9, s7, 31
	v_bitop3_b32 v10, v2, v3, 48 bitop3:0x6c
	v_lshrrev_b32_e32 v3, 1, v0
	s_lshr_b32 s9, s9, 26
	v_and_b32_e32 v12, 24, v3
	v_lshrrev_b32_e32 v3, 5, v0
	s_add_i32 s9, s7, s9
	v_and_b32_e32 v3, 4, v3
	v_bfe_u32 v5, v0, 2, 2
	s_ashr_i32 s10, s9, 6
	s_andn2_b32 s9, s9, 63
	v_bfe_u32 v4, v0, 2, 4
	v_and_b32_e32 v11, 64, v0
	v_or3_b32 v3, v3, v5, v12
	v_lshrrev_b32_e32 v5, 3, v0
	s_sub_i32 s9, s7, s9
	v_or_b32_e32 v2, v10, v11
	v_and_or_b32 v6, v5, 48, v4
	v_and_or_b32 v5, v5, 32, v3
	s_bfe_u32 s7, s9, 0x10007
	v_lshrrev_b32_e32 v2, 1, v2
	v_mul_u32_u24_e32 v5, 0x2b00, v5
	s_add_i32 s11, s9, s7
	v_or_b32_e32 v5, v5, v2
	s_bfe_i32 s7, s11, 0x80000
	s_and_b32 s11, s11, 0xfc
	s_waitcnt vmcnt(0)
	v_lshlrev_b32_e32 v152, 1, v5
	v_bfe_u32 v5, v0, 3, 25
	s_sub_i32 s9, s9, s11
	v_or_b32_e32 v5, 64, v5
	s_movk_i32 s6, 0x70
	s_lshl_b32 s10, s10, 2
	s_sext_i32_i16 s12, s7
	s_sext_i32_i8 s9, s9
	s_lshr_b32 s2, s8, 6
	v_and_or_b32 v4, v5, s6, v4
	s_movk_i32 s6, 0x60
	s_add_i32 s47, s10, s9
	s_ashr_i32 s10, s12, 2
	v_and_or_b32 v3, v5, s6, v3
	s_lshr_b32 s6, s8, 8
	s_lshl_b32 s34, s2, 10
	s_lshr_b32 s7, s12, 2
	s_mul_hi_i32 s11, s10, 0x560000
	s_mul_i32 s10, s10, 0x560000
	s_add_u32 s26, s31, s10
	s_addc_u32 s27, s33, s11
	s_add_i32 s35, s34, 0
	v_mul_u32_u24_e32 v13, 0x2b00, v6
	v_mul_u32_u24_e32 v14, 0x2b00, v4
	v_mul_u32_u24_e32 v3, 0x2b00, v3
	s_add_i32 m0, s35, 0x10000
	v_or_b32_e32 v6, v2, v13
	v_or_b32_e32 v4, v14, v2
	v_or_b32_e32 v2, v3, v2
	global_load_lds_dwordx4 v152, s[26:27]
	s_add_i32 m0, s35, 0x12000
	v_lshlrev_b32_e32 v156, 1, v2
	s_add_u32 s10, s26, 0x2b0000
	global_load_lds_dwordx4 v156, s[26:27]
	s_addc_u32 s11, s27, 0
	s_add_i32 m0, s35, 0x14000
	s_mul_i32 s13, s47, 0x560000
	global_load_lds_dwordx4 v152, s[10:11]
	s_add_i32 m0, s35, 0x16000
	s_mul_hi_i32 s9, s47, 0x560000
	s_add_u32 s24, s21, s13
	s_addc_u32 s25, s30, s9
	s_add_i32 s36, s35, 0x2000
	v_lshlrev_b32_e32 v150, 1, v6
	global_load_lds_dwordx4 v156, s[10:11]
	s_mov_b32 m0, s35
	s_add_u32 s10, s24, 0x2b0000
	v_lshlrev_b32_e32 v154, 1, v4
	global_load_lds_dwordx4 v150, s[24:25]
	s_mov_b32 m0, s36
	s_addc_u32 s11, s25, 0
	s_add_i32 s37, s35, 0x4000
	global_load_lds_dwordx4 v154, s[24:25]
	s_mov_b32 m0, s37
	s_add_i32 s38, s35, 0x6000
	global_load_lds_dwordx4 v150, s[10:11]
	s_mov_b32 m0, s38
	s_load_dwordx4 s[12:15], s[0:1], 0xb0
	global_load_lds_dwordx4 v154, s[10:11]
	v_mov_b32_e32 v153, 0
	v_mov_b32_e32 v157, v153
	v_mov_b32_e32 v151, v153
	v_mov_b32_e32 v155, v153
	s_cmp_eq_u32 s6, 1
	s_mov_b32 s39, 0
	v_lshl_add_u64 v[8:9], s[26:27], 0, v[152:153]
	v_lshl_add_u64 v[6:7], s[26:27], 0, v[156:157]
	v_lshl_add_u64 v[2:3], s[24:25], 0, v[150:151]
	s_cselect_b64 s[10:11], -1, 0
	s_cmp_lg_u32 s6, 1
	v_lshl_add_u64 v[4:5], s[24:25], 0, v[154:155]
	s_cbranch_scc1 .LBB0_941
	s_barrier

.LBB0_949:
	s_ashr_i32 s6, s22, 3
	s_add_i32 s6, s28, s6
	s_ashr_i32 s7, s6, 31
	s_lshr_b32 s7, s7, 26
	s_add_i32 s7, s6, s7
	s_ashr_i32 s22, s7, 6
	s_lshl_b32 s22, s22, 2
	s_sub_i32 s23, 64, s22
	s_min_i32 s23, s23, 4
	s_abs_i32 s28, s23
	v_cvt_f32_u32_e32 v2, s28
	s_sub_i32 s45, 0, s28
	s_andn2_b32 s7, s7, 63
	s_sub_i32 s6, s6, s7
	v_rcp_iflag_f32_e32 v2, v2
	s_abs_i32 s7, s6
	s_xor_b32 s29, s6, s23
	s_ashr_i32 s29, s29, 31
	v_mul_f32_e32 v2, 0x4f7ffffe, v2
	v_cvt_u32_f32_e32 v2, v2
	s_nop 0
	v_readfirstlane_b32 s46, v2
	s_mul_i32 s45, s45, s46
	s_mul_hi_u32 s45, s46, s45
	s_add_i32 s46, s46, s45
	s_mul_hi_u32 s45, s7, s46
	s_mul_i32 s46, s45, s28
	s_sub_i32 s7, s7, s46
	s_add_i32 s48, s45, 1
	s_sub_i32 s46, s7, s28
	s_cmp_ge_u32 s7, s28
	s_cselect_b32 s45, s48, s45
	s_cselect_b32 s7, s46, s7
	s_add_i32 s46, s45, 1
	s_cmp_ge_u32 s7, s28
	s_cselect_b32 s7, s46, s45
	s_xor_b32 s7, s7, s29
	s_sub_i32 s45, s7, s29
	s_mul_i32 s7, s45, s23
	s_sub_i32 s6, s6, s7
	s_add_i32 s46, s22, s6

.LBB0_2353:
	s_add_u32 s23, s74, 0x23510000
	s_addc_u32 s33, s75, 0
	s_add_u32 s34, s74, 0x60150000
	s_addc_u32 s35, s75, 0
	s_add_i32 s7, s8, s7
	v_lshlrev_b32_e32 v2, 4, v0
	v_and_b32_e32 v3, 32, v0
	s_ashr_i32 s8, s7, 31
	v_bitop3_b32 v10, v2, v3, 48 bitop3:0x6c
	v_lshrrev_b32_e32 v3, 1, v0
	s_lshr_b32 s8, s8, 26
	v_and_b32_e32 v12, 24, v3
	v_lshrrev_b32_e32 v3, 5, v0
	s_add_i32 s8, s7, s8
	v_and_b32_e32 v3, 4, v3
	v_bfe_u32 v5, v0, 2, 2
	s_ashr_i32 s9, s8, 6
	s_and_b32 s8, s8, 0xffc0
	v_bfe_u32 v4, v0, 2, 4
	v_and_b32_e32 v11, 64, v0
	v_or3_b32 v3, v3, v5, v12
	v_lshrrev_b32_e32 v5, 3, v0
	s_sub_i32 s8, s7, s8
	v_or_b32_e32 v2, v10, v11
	v_and_or_b32 v6, v5, 48, v4
	v_and_or_b32 v5, v5, 32, v3
	s_bfe_u32 s7, s8, 0x10007
	v_lshrrev_b32_e32 v2, 1, v2
	v_mul_u32_u24_e32 v5, 0x2b00, v5
	s_add_i32 s10, s8, s7
	v_or_b32_e32 v5, v5, v2
	s_bfe_i32 s7, s10, 0x80000
	s_and_b32 s10, s10, 0xfc
	s_waitcnt vmcnt(0)
	v_lshlrev_b32_e32 v152, 1, v5
	v_bfe_u32 v5, v0, 3, 25
	s_sub_i32 s8, s8, s10
	v_or_b32_e32 v5, 64, v5
	s_movk_i32 s6, 0x70
	s_lshl_b32 s9, s9, 2
	s_sext_i32_i16 s11, s7
	s_sext_i32_i8 s8, s8
	s_lshr_b32 s2, s20, 6
	v_and_or_b32 v4, v5, s6, v4
	s_movk_i32 s6, 0x60
	s_add_i32 s49, s9, s8
	s_ashr_i32 s8, s11, 2
	v_and_or_b32 v3, v5, s6, v3
	s_lshr_b32 s6, s20, 8
	s_lshl_b32 s36, s2, 10
	s_lshr_b32 s7, s11, 2
	s_mul_hi_i32 s9, s8, 0x560000
	s_mul_i32 s8, s8, 0x560000
	s_add_u32 s28, s34, s8
	s_addc_u32 s29, s35, s9
	s_add_i32 s37, s36, 0
	v_mul_u32_u24_e32 v13, 0x2b00, v6
	v_mul_u32_u24_e32 v14, 0x2b00, v4
	v_mul_u32_u24_e32 v3, 0x2b00, v3
	s_add_i32 m0, s37, 0x10000
	v_or_b32_e32 v6, v2, v13
	v_or_b32_e32 v4, v14, v2
	v_or_b32_e32 v2, v3, v2
	global_load_lds_dwordx4 v152, s[28:29]
	s_add_i32 m0, s37, 0x12000
	v_lshlrev_b32_e32 v156, 1, v2
	s_add_u32 s8, s28, 0x2b0000
	global_load_lds_dwordx4 v156, s[28:29]
	s_addc_u32 s9, s29, 0
	s_add_i32 m0, s37, 0x14000
	s_mul_i32 s14, s49, 0x560000
	global_load_lds_dwordx4 v152, s[8:9]
	s_add_i32 m0, s37, 0x16000
	s_mul_hi_i32 s10, s49, 0x560000
	s_add_u32 s26, s23, s14
	s_addc_u32 s27, s33, s10
	s_add_i32 s38, s37, 0x2000
	v_lshlrev_b32_e32 v150, 1, v6
	global_load_lds_dwordx4 v156, s[8:9]
	s_mov_b32 m0, s37
	s_add_u32 s8, s26, 0x2b0000
	v_lshlrev_b32_e32 v154, 1, v4
	global_load_lds_dwordx4 v150, s[26:27]
	s_mov_b32 m0, s38
	s_addc_u32 s9, s27, 0
	s_add_i32 s39, s37, 0x4000
	global_load_lds_dwordx4 v154, s[26:27]
	s_mov_b32 m0, s39
	s_add_i32 s40, s37, 0x6000
	global_load_lds_dwordx4 v150, s[8:9]
	s_mov_b32 m0, s40
	v_mov_b32_e32 v153, 0
	global_load_lds_dwordx4 v154, s[8:9]
	s_load_dwordx4 s[8:11], s[0:1], 0xb0
	v_mov_b32_e32 v157, v153
	v_mov_b32_e32 v151, v153
	v_mov_b32_e32 v155, v153
	s_cmp_eq_u32 s6, 1
	s_mov_b32 s41, 0
	v_lshl_add_u64 v[8:9], s[28:29], 0, v[152:153]
	v_lshl_add_u64 v[6:7], s[28:29], 0, v[156:157]
	v_lshl_add_u64 v[2:3], s[26:27], 0, v[150:151]
	s_cselect_b64 s[14:15], -1, 0
	s_cmp_lg_u32 s6, 1
	v_lshl_add_u64 v[4:5], s[26:27], 0, v[154:155]
	s_cbranch_scc1 .LBB0_2355
	s_barrier

.LBB0_2363:
	s_ashr_i32 s6, s24, 3
	s_add_i32 s6, s30, s6
	s_ashr_i32 s7, s6, 31
	s_lshr_b32 s7, s7, 26
	s_add_i32 s7, s6, s7
	s_ashr_i32 s24, s7, 6
	s_lshl_b32 s24, s24, 2
	s_sub_i32 s25, 64, s24
	s_min_i32 s25, s25, 4
	s_abs_i32 s30, s25
	v_cvt_f32_u32_e32 v2, s30
	s_sub_i32 s47, 0, s30
	s_andn2_b32 s7, s7, 63
	s_sub_i32 s6, s6, s7
	v_rcp_iflag_f32_e32 v2, v2
	s_abs_i32 s7, s6
	s_xor_b32 s31, s6, s25
	s_ashr_i32 s31, s31, 31
	v_mul_f32_e32 v2, 0x4f7ffffe, v2
	v_cvt_u32_f32_e32 v2, v2
	s_nop 0
	v_readfirstlane_b32 s48, v2
	s_mul_i32 s47, s47, s48
	s_mul_hi_u32 s47, s48, s47
	s_add_i32 s48, s48, s47
	s_mul_hi_u32 s47, s7, s48
	s_mul_i32 s48, s47, s30
	s_sub_i32 s7, s7, s48
	s_add_i32 s50, s47, 1
	s_sub_i32 s48, s7, s30
	s_cmp_ge_u32 s7, s30
	s_cselect_b32 s47, s50, s47
	s_cselect_b32 s7, s48, s7
	s_add_i32 s48, s47, 1
	s_cmp_ge_u32 s7, s30
	s_cselect_b32 s7, s48, s47
	s_xor_b32 s7, s7, s31
	s_sub_i32 s47, s7, s31
	s_mul_i32 s7, s47, s25
	s_sub_i32 s6, s6, s7
	s_add_i32 s48, s24, s6
